# scan remap + convert hoists + batched row loads in P0 x-conv + batched rstd table loads
# speedup vs baseline: 1.0056x; 1.0056x over previous
; #define LAS __attribute__((address_space(3)))
; __device__ __forceinline__ void build_rstd_table(Frame& F, const float* part, const int pm0) {
;     if (F.tid < 256) { const f32x4* p = (const f32x4*)(part + (size_t)(pm0 * 256 + F.tid) * 32); float s = 0.f;
; #pragma unroll
;         for (int q = 0; q < 8; ++q) { const f32x4 a = p[q]; s += (a[0] + a[1]) + (a[2] + a[3]); }
;         ((LAS float*)(F.lds + RSTD_TAB_OFF))[F.tid] = 1.0f / sqrtf(s * (1.0f / 2048.0f) + RMS_EPS); }
.LBB0_161:
	s_movk_i32 s4, 0x100
	v_cmp_gt_i32_e32 vcc, s4, v97
	s_and_saveexec_b64 s[4:5], vcc
	s_cbranch_execz .LBB0_163
	v_lshl_add_u32 v0, s8, 8, v97
	s_waitcnt lgkmcnt(0)
	v_ashrrev_i32_e32 v1, 31, v0
	v_lshlrev_b64 v[0:1], 7, v[0:1]
	v_lshl_add_u64 v[8:9], s[50:51], 0, v[0:1]
	flat_load_dwordx4 v[0:3], v[8:9]
	flat_load_dwordx4 v[4:7], v[8:9] offset:16
	flat_load_dwordx4 v[16:19], v[8:9] offset:32
	flat_load_dwordx4 v[20:23], v[8:9] offset:48
	flat_load_dwordx4 v[24:27], v[8:9] offset:64
	flat_load_dwordx4 v[28:31], v[8:9] offset:80
	flat_load_dwordx4 v[32:35], v[8:9] offset:96
	flat_load_dwordx4 v[36:39], v[8:9] offset:112
	s_waitcnt vmcnt(0) lgkmcnt(0)
	v_mov_b32_e32 v10, v0
	v_mov_b32_e32 v11, v4
	v_mov_b32_e32 v4, v1
	v_pk_add_f32 v[0:1], v[10:11], v[4:5]
	v_mov_b32_e32 v4, v2
	v_mov_b32_e32 v5, v6
	v_mov_b32_e32 v6, v3
	v_pk_add_f32 v[2:3], v[4:5], v[6:7]
	s_nop 0
	v_pk_add_f32 v[0:1], v[0:1], v[2:3]
	s_nop 0
	v_add_f32_e32 v0, 0, v0
	v_add_f32_e32 v4, v0, v1
	v_mov_b32_e32 v0, v16
	v_mov_b32_e32 v1, v17
	v_mov_b32_e32 v2, v18
	v_mov_b32_e32 v3, v19
	v_mov_b32_e32 v6, v1
	v_mov_b32_e32 v7, v2
	v_mov_b32_e32 v1, v3
	v_pk_add_f32 v[0:1], v[6:7], v[0:1]
	s_nop 0
	v_pk_add_f32 v[6:7], v[0:1], v[0:1] op_sel:[0,1] op_sel_hi:[1,0]
	v_mov_b32_e32 v0, v20
	v_mov_b32_e32 v1, v21
	v_mov_b32_e32 v2, v22
	v_mov_b32_e32 v3, v23
	v_add_f32_e32 v10, v0, v1
	v_add_f32_e32 v12, v2, v3
	v_mov_b32_e32 v0, v24
	v_mov_b32_e32 v1, v25
	v_mov_b32_e32 v2, v26
	v_mov_b32_e32 v3, v27
	v_mov_b32_e32 v5, v0
	v_mov_b32_e32 v7, v1
	v_mov_b32_e32 v11, v2
	v_mov_b32_e32 v13, v3
	v_pk_add_f32 v[0:1], v[4:5], v[6:7]
	v_pk_add_f32 v[2:3], v[10:11], v[12:13]
	s_nop 0
	v_pk_add_f32 v[0:1], v[0:1], v[2:3]
	s_nop 0
	v_pk_add_f32 v[4:5], v[0:1], v[0:1] op_sel:[0,1] op_sel_hi:[1,0]
	v_mov_b32_e32 v0, v28
	v_mov_b32_e32 v1, v29
	v_mov_b32_e32 v2, v30
	v_mov_b32_e32 v3, v31
	v_mov_b32_e32 v6, v1
	v_mov_b32_e32 v7, v2
	v_mov_b32_e32 v1, v3
	v_pk_add_f32 v[0:1], v[6:7], v[0:1]
	s_nop 0
	v_pk_add_f32 v[6:7], v[0:1], v[0:1] op_sel:[0,1] op_sel_hi:[1,0]
	v_mov_b32_e32 v0, v32
	v_mov_b32_e32 v1, v33
	v_mov_b32_e32 v2, v34
	v_mov_b32_e32 v3, v35
	v_add_f32_e32 v10, v0, v1
	v_add_f32_e32 v12, v2, v3
	v_mov_b32_e32 v0, v36
	v_mov_b32_e32 v1, v37
	v_mov_b32_e32 v2, v38
	v_mov_b32_e32 v3, v39
	v_mov_b32_e32 v5, v0
	v_mov_b32_e32 v7, v1
	v_mov_b32_e32 v11, v2
	v_mov_b32_e32 v13, v3
	v_pk_add_f32 v[0:1], v[4:5], v[6:7]
	v_pk_add_f32 v[2:3], v[10:11], v[12:13]
	s_nop 0
	v_pk_add_f32 v[0:1], v[0:1], v[2:3]
	s_nop 0
	v_add_f32_e32 v0, v0, v1
	v_fmamk_f32 v0, v0, 0x3a000000, v237
	v_cmp_gt_f32_e32 vcc, s89, v0
	v_mul_f32_e32 v1, 0x4f800000, v0
	s_nop 0
	v_cndmask_b32_e32 v0, v0, v1, vcc
	v_sqrt_f32_e32 v1, v0
	s_nop 0
	v_add_u32_e32 v2, -1, v1
	v_fma_f32 v3, -v2, v1, v0
	v_cmp_ge_f32_e64 s[40:41], 0, v3
	v_add_u32_e32 v3, 1, v1
	s_nop 0
	v_cndmask_b32_e64 v2, v1, v2, s[40:41]
	v_fma_f32 v1, -v3, v1, v0
	v_cmp_lt_f32_e64 s[40:41], 0, v1
	s_nop 1
	v_cndmask_b32_e64 v1, v2, v3, s[40:41]
	v_mul_f32_e32 v2, 0x37800000, v1
	v_cndmask_b32_e32 v1, v1, v2, vcc
	v_cmp_class_f32_e32 vcc, v0, v238
	s_nop 1
	v_cndmask_b32_e32 v0, v1, v0, vcc
	v_div_scale_f32 v1, s[10:11], v0, v0, 1.0
	v_rcp_f32_e32 v2, v1
	s_nop 0
	v_fma_f32 v3, -v1, v2, 1.0
	v_fmac_f32_e32 v2, v3, v2
	v_div_scale_f32 v3, vcc, 1.0, v0, 1.0
	v_mul_f32_e32 v4, v3, v2
	v_fma_f32 v5, -v1, v4, v3
	v_fmac_f32_e32 v4, v5, v2
	v_fma_f32 v1, -v1, v4, v3
	v_div_fmas_f32 v1, v1, v2, v4
	v_div_fixup_f32 v0, v1, v0, 1.0
	v_lshl_add_u32 v1, v97, 2, 0
	v_add_u32_e32 v1, 0x20000, v1
	ds_write_b32 v1, v0

; #define LAS __attribute__((address_space(3)))
; __device__ __forceinline__ void build_rstd_table(Frame& F, const float* part, const int pm0) {
;     if (F.tid < 256) { const f32x4* p = (const f32x4*)(part + (size_t)(pm0 * 256 + F.tid) * 32); float s = 0.f;
; #pragma unroll
;         for (int q = 0; q < 8; ++q) { const f32x4 a = p[q]; s += (a[0] + a[1]) + (a[2] + a[3]); }
;         ((LAS float*)(F.lds + RSTD_TAB_OFF))[F.tid] = 1.0f / sqrtf(s * (1.0f / 2048.0f) + RMS_EPS); }
.LBB0_222:
	s_movk_i32 s4, 0x100
	v_cmp_gt_i32_e32 vcc, s4, v97
	s_and_saveexec_b64 s[4:5], vcc
	s_cbranch_execz .LBB0_224
	v_readlane_b32 s8, v255, 23
	s_nop 1
	v_lshl_add_u32 v0, s8, 8, v97
	s_waitcnt lgkmcnt(0)
	v_ashrrev_i32_e32 v1, 31, v0
	v_lshlrev_b64 v[0:1], 7, v[0:1]
	v_lshl_add_u64 v[8:9], s[50:51], 0, v[0:1]
	flat_load_dwordx4 v[0:3], v[8:9]
	flat_load_dwordx4 v[4:7], v[8:9] offset:16
	flat_load_dwordx4 v[16:19], v[8:9] offset:32
	flat_load_dwordx4 v[20:23], v[8:9] offset:48
	flat_load_dwordx4 v[24:27], v[8:9] offset:64
	flat_load_dwordx4 v[28:31], v[8:9] offset:80
	flat_load_dwordx4 v[32:35], v[8:9] offset:96
	flat_load_dwordx4 v[36:39], v[8:9] offset:112
	s_waitcnt vmcnt(0) lgkmcnt(0)
	v_mov_b32_e32 v10, v0
	v_mov_b32_e32 v11, v4
	v_mov_b32_e32 v4, v1
	v_pk_add_f32 v[0:1], v[10:11], v[4:5]
	v_mov_b32_e32 v4, v2
	v_mov_b32_e32 v5, v6
	v_mov_b32_e32 v6, v3
	v_pk_add_f32 v[2:3], v[4:5], v[6:7]
	s_nop 0
	v_pk_add_f32 v[0:1], v[0:1], v[2:3]
	s_nop 0
	v_add_f32_e32 v0, 0, v0
	v_add_f32_e32 v4, v0, v1
	v_mov_b32_e32 v0, v16
	v_mov_b32_e32 v1, v17
	v_mov_b32_e32 v2, v18
	v_mov_b32_e32 v3, v19
	v_mov_b32_e32 v6, v1
	v_mov_b32_e32 v7, v2
	v_mov_b32_e32 v1, v3
	v_pk_add_f32 v[0:1], v[6:7], v[0:1]
	s_nop 0
	v_pk_add_f32 v[6:7], v[0:1], v[0:1] op_sel:[0,1] op_sel_hi:[1,0]
	v_mov_b32_e32 v0, v20
	v_mov_b32_e32 v1, v21
	v_mov_b32_e32 v2, v22
	v_mov_b32_e32 v3, v23
	v_add_f32_e32 v10, v0, v1
	v_add_f32_e32 v12, v2, v3
	v_mov_b32_e32 v0, v24
	v_mov_b32_e32 v1, v25
	v_mov_b32_e32 v2, v26
	v_mov_b32_e32 v3, v27
	v_mov_b32_e32 v5, v0
	v_mov_b32_e32 v7, v1
	v_mov_b32_e32 v11, v2
	v_mov_b32_e32 v13, v3
	v_pk_add_f32 v[0:1], v[4:5], v[6:7]
	v_pk_add_f32 v[2:3], v[10:11], v[12:13]
	s_nop 0
	v_pk_add_f32 v[0:1], v[0:1], v[2:3]
	s_nop 0
	v_pk_add_f32 v[4:5], v[0:1], v[0:1] op_sel:[0,1] op_sel_hi:[1,0]
	v_mov_b32_e32 v0, v28
	v_mov_b32_e32 v1, v29
	v_mov_b32_e32 v2, v30
	v_mov_b32_e32 v3, v31
	v_mov_b32_e32 v6, v1
	v_mov_b32_e32 v7, v2
	v_mov_b32_e32 v1, v3
	v_pk_add_f32 v[0:1], v[6:7], v[0:1]
	s_nop 0
	v_pk_add_f32 v[6:7], v[0:1], v[0:1] op_sel:[0,1] op_sel_hi:[1,0]
	v_mov_b32_e32 v0, v32
	v_mov_b32_e32 v1, v33
	v_mov_b32_e32 v2, v34
	v_mov_b32_e32 v3, v35
	v_add_f32_e32 v10, v0, v1
	v_add_f32_e32 v12, v2, v3
	v_mov_b32_e32 v0, v36
	v_mov_b32_e32 v1, v37
	v_mov_b32_e32 v2, v38
	v_mov_b32_e32 v3, v39
	v_mov_b32_e32 v5, v0
	v_mov_b32_e32 v7, v1
	v_mov_b32_e32 v11, v2
	v_mov_b32_e32 v13, v3
	v_pk_add_f32 v[0:1], v[4:5], v[6:7]
	v_pk_add_f32 v[2:3], v[10:11], v[12:13]
	s_nop 0
	v_pk_add_f32 v[0:1], v[0:1], v[2:3]
	s_nop 0
	v_add_f32_e32 v0, v0, v1
	v_fmamk_f32 v0, v0, 0x3a000000, v237
	v_cmp_gt_f32_e32 vcc, s89, v0
	v_mul_f32_e32 v1, 0x4f800000, v0
	s_nop 0
	v_cndmask_b32_e32 v0, v0, v1, vcc
	v_sqrt_f32_e32 v1, v0
	s_nop 0
	v_add_u32_e32 v2, -1, v1
	v_fma_f32 v3, -v2, v1, v0
	v_cmp_ge_f32_e64 s[40:41], 0, v3
	v_add_u32_e32 v3, 1, v1
	s_nop 0
	v_cndmask_b32_e64 v2, v1, v2, s[40:41]
	v_fma_f32 v1, -v3, v1, v0
	v_cmp_lt_f32_e64 s[40:41], 0, v1
	s_nop 1
	v_cndmask_b32_e64 v1, v2, v3, s[40:41]
	v_mul_f32_e32 v2, 0x37800000, v1
	v_cndmask_b32_e32 v1, v1, v2, vcc
	v_cmp_class_f32_e32 vcc, v0, v238
	s_nop 1
	v_cndmask_b32_e32 v0, v1, v0, vcc
	v_div_scale_f32 v1, s[8:9], v0, v0, 1.0
	v_rcp_f32_e32 v2, v1
	s_nop 0
	v_fma_f32 v3, -v1, v2, 1.0
	v_fmac_f32_e32 v2, v3, v2
	v_div_scale_f32 v3, vcc, 1.0, v0, 1.0
	v_mul_f32_e32 v4, v3, v2
	v_fma_f32 v5, -v1, v4, v3
	v_fmac_f32_e32 v4, v5, v2
	v_fma_f32 v1, -v1, v4, v3
	v_div_fmas_f32 v1, v1, v2, v4
	v_div_fixup_f32 v0, v1, v0, 1.0
	v_lshl_add_u32 v1, v97, 2, 0
	v_add_u32_e32 v1, 0x20000, v1
	ds_write_b32 v1, v0

; #define LAS __attribute__((address_space(3)))
; __device__ __forceinline__ void build_rstd_table(Frame& F, const float* part, const int pm0) {
;     if (F.tid < 256) { const f32x4* p = (const f32x4*)(part + (size_t)(pm0 * 256 + F.tid) * 32); float s = 0.f;
; #pragma unroll
;         for (int q = 0; q < 8; ++q) { const f32x4 a = p[q]; s += (a[0] + a[1]) + (a[2] + a[3]); }
;         ((LAS float*)(F.lds + RSTD_TAB_OFF))[F.tid] = 1.0f / sqrtf(s * (1.0f / 2048.0f) + RMS_EPS); }
.LBB0_993:
	s_movk_i32 s4, 0x100
	v_cmp_gt_i32_e32 vcc, s4, v0
	s_and_saveexec_b64 s[4:5], vcc
	s_cbranch_execz .LBB0_995
	v_readlane_b32 s8, v255, 27
	s_nop 1
	v_lshl_add_u32 v2, s8, 8, v0
	v_ashrrev_i32_e32 v3, 31, v2
	v_lshlrev_b64 v[2:3], 7, v[2:3]
	v_lshl_add_u64 v[2:3], s[14:15], 0, v[2:3]
	s_mov_b64 s[8:9], 0x3b900000
	v_lshl_add_u64 v[10:11], v[2:3], 0, s[8:9]
	v_add_co_u32_e32 v2, vcc, 0x3b900000, v2
	v_lshl_add_u32 v0, v0, 2, 0
	s_nop 0
	v_addc_co_u32_e32 v3, vcc, 0, v3, vcc
	flat_load_dwordx4 v[2:5], v[2:3]
	s_nop 0
	flat_load_dwordx4 v[6:9], v[10:11] offset:16
	flat_load_dwordx4 v[16:19], v[10:11] offset:32
	flat_load_dwordx4 v[20:23], v[10:11] offset:48
	flat_load_dwordx4 v[24:27], v[10:11] offset:64
	flat_load_dwordx4 v[28:31], v[10:11] offset:80
	flat_load_dwordx4 v[32:35], v[10:11] offset:96
	flat_load_dwordx4 v[36:39], v[10:11] offset:112
	v_add_u32_e32 v0, 0x20000, v0
	s_waitcnt vmcnt(0) lgkmcnt(0)
	v_mov_b32_e32 v12, v2
	v_mov_b32_e32 v13, v6
	v_mov_b32_e32 v6, v3
	v_pk_add_f32 v[2:3], v[12:13], v[6:7]
	v_mov_b32_e32 v6, v4
	v_mov_b32_e32 v7, v8
	v_mov_b32_e32 v8, v5
	v_pk_add_f32 v[4:5], v[6:7], v[8:9]
	s_nop 0
	v_pk_add_f32 v[2:3], v[2:3], v[4:5]
	s_nop 0
	v_add_f32_e32 v1, 0, v2
	v_add_f32_e32 v6, v1, v3
	v_mov_b32_e32 v2, v16
	v_mov_b32_e32 v3, v17
	v_mov_b32_e32 v4, v18
	v_mov_b32_e32 v5, v19
	v_mov_b32_e32 v8, v3
	v_mov_b32_e32 v9, v4
	v_mov_b32_e32 v3, v5
	v_pk_add_f32 v[2:3], v[8:9], v[2:3]
	s_nop 0
	v_pk_add_f32 v[8:9], v[2:3], v[2:3] op_sel:[0,1] op_sel_hi:[1,0]
	v_mov_b32_e32 v2, v20
	v_mov_b32_e32 v3, v21
	v_mov_b32_e32 v4, v22
	v_mov_b32_e32 v5, v23
	v_add_f32_e32 v12, v2, v3
	v_add_f32_e32 v14, v4, v5
	v_mov_b32_e32 v2, v24
	v_mov_b32_e32 v3, v25
	v_mov_b32_e32 v4, v26
	v_mov_b32_e32 v5, v27
	v_mov_b32_e32 v7, v2
	v_mov_b32_e32 v9, v3
	v_mov_b32_e32 v13, v4
	v_mov_b32_e32 v15, v5
	v_pk_add_f32 v[2:3], v[6:7], v[8:9]
	v_pk_add_f32 v[4:5], v[12:13], v[14:15]
	s_nop 0
	v_pk_add_f32 v[2:3], v[2:3], v[4:5]
	s_nop 0
	v_pk_add_f32 v[6:7], v[2:3], v[2:3] op_sel:[0,1] op_sel_hi:[1,0]
	v_mov_b32_e32 v2, v28
	v_mov_b32_e32 v3, v29
	v_mov_b32_e32 v4, v30
	v_mov_b32_e32 v5, v31
	v_mov_b32_e32 v8, v3
	v_mov_b32_e32 v9, v4
	v_mov_b32_e32 v3, v5
	v_pk_add_f32 v[2:3], v[8:9], v[2:3]
	s_nop 0
	v_pk_add_f32 v[8:9], v[2:3], v[2:3] op_sel:[0,1] op_sel_hi:[1,0]
	v_mov_b32_e32 v2, v32
	v_mov_b32_e32 v3, v33
	v_mov_b32_e32 v4, v34
	v_mov_b32_e32 v5, v35
	v_add_f32_e32 v12, v2, v3
	v_add_f32_e32 v14, v4, v5
	v_mov_b32_e32 v2, v36
	v_mov_b32_e32 v3, v37
	v_mov_b32_e32 v4, v38
	v_mov_b32_e32 v5, v39
	v_mov_b32_e32 v7, v2
	v_mov_b32_e32 v9, v3
	v_mov_b32_e32 v13, v4
	v_mov_b32_e32 v15, v5
	v_pk_add_f32 v[2:3], v[6:7], v[8:9]
	v_pk_add_f32 v[4:5], v[12:13], v[14:15]
	s_nop 0
	v_pk_add_f32 v[2:3], v[2:3], v[4:5]
	s_nop 0
	v_add_f32_e32 v1, v2, v3
	v_fmamk_f32 v1, v1, 0x3a000000, v237
	v_cmp_gt_f32_e32 vcc, s89, v1
	v_mul_f32_e32 v2, 0x4f800000, v1
	s_nop 0
	v_cndmask_b32_e32 v1, v1, v2, vcc
	v_sqrt_f32_e32 v2, v1
	s_nop 0
	v_add_u32_e32 v3, -1, v2
	v_fma_f32 v4, -v3, v2, v1
	v_cmp_ge_f32_e64 s[40:41], 0, v4
	v_add_u32_e32 v4, 1, v2
	s_nop 0
	v_cndmask_b32_e64 v3, v2, v3, s[40:41]
	v_fma_f32 v2, -v4, v2, v1
	v_cmp_lt_f32_e64 s[40:41], 0, v2
	s_nop 1
	v_cndmask_b32_e64 v2, v3, v4, s[40:41]
	v_mul_f32_e32 v3, 0x37800000, v2
	v_cndmask_b32_e32 v2, v2, v3, vcc
	v_cmp_class_f32_e32 vcc, v1, v238
	s_nop 1
	v_cndmask_b32_e32 v1, v2, v1, vcc
	v_div_scale_f32 v2, s[8:9], v1, v1, 1.0
	v_rcp_f32_e32 v3, v2
	s_nop 0
	v_fma_f32 v4, -v2, v3, 1.0
	v_fmac_f32_e32 v3, v4, v3
	v_div_scale_f32 v4, vcc, 1.0, v1, 1.0
	v_mul_f32_e32 v5, v4, v3
	v_fma_f32 v6, -v2, v5, v4
	v_fmac_f32_e32 v5, v6, v3
	v_fma_f32 v2, -v2, v5, v4
	v_div_fmas_f32 v2, v2, v3, v5
	v_div_fixup_f32 v1, v2, v1, 1.0
	ds_write_b32 v0, v1
